# GEMM accumulator zeroing between tiles with 64-bit moves (half the instructions)
# speedup vs baseline: 1.0086x; 1.0033x over previous
.LBB0_132:
	s_add_u32 s34, s28, 0x100
	v_mov_b32_e32 v0, 0
	s_addc_u32 s79, s29, 0
	s_mov_b32 s84, -2
	v_mov_b32_e32 v1, v0
	v_mov_b64_e32 v[2:3], 0
	v_mov_b64_e32 v[4:5], 0
	v_mov_b64_e32 v[6:7], 0
	v_mov_b64_e32 v[8:9], 0
	v_mov_b64_e32 v[10:11], 0
	v_mov_b64_e32 v[12:13], 0
	v_mov_b64_e32 v[14:15], 0
	v_mov_b64_e32 v[22:23], 0
	v_mov_b64_e32 v[24:25], 0
	v_mov_b64_e32 v[26:27], 0
	v_mov_b64_e32 v[28:29], 0
	v_mov_b64_e32 v[34:35], 0
	v_mov_b64_e32 v[36:37], 0
	v_mov_b64_e32 v[42:43], 0
	v_mov_b64_e32 v[44:45], 0
	v_mov_b64_e32 v[18:19], 0
	v_mov_b64_e32 v[20:21], 0
	v_mov_b64_e32 v[30:31], 0
	v_mov_b64_e32 v[32:33], 0
	v_mov_b64_e32 v[38:39], 0
	v_mov_b64_e32 v[40:41], 0
	v_mov_b64_e32 v[46:47], 0
	v_mov_b64_e32 v[48:49], 0
	v_mov_b64_e32 v[50:51], 0
	v_mov_b64_e32 v[52:53], 0
	v_mov_b64_e32 v[54:55], 0
	v_mov_b64_e32 v[56:57], 0
	v_mov_b64_e32 v[58:59], 0
	v_mov_b64_e32 v[60:61], 0
	v_mov_b64_e32 v[62:63], 0
	v_mov_b64_e32 v[64:65], 0
	v_mov_b64_e32 v[66:67], 0
	v_mov_b64_e32 v[68:69], 0
	v_mov_b64_e32 v[70:71], 0
	v_mov_b64_e32 v[72:73], 0
	v_mov_b64_e32 v[78:79], 0
	v_mov_b64_e32 v[80:81], 0
	v_mov_b64_e32 v[82:83], 0
	v_mov_b64_e32 v[84:85], 0
	v_mov_b64_e32 v[94:95], 0
	v_mov_b64_e32 v[96:97], 0
	v_mov_b64_e32 v[98:99], 0
	v_mov_b64_e32 v[100:101], 0
	v_mov_b64_e32 v[110:111], 0
	v_mov_b64_e32 v[112:113], 0
	v_mov_b64_e32 v[114:115], 0
	v_mov_b64_e32 v[116:117], 0
	v_mov_b64_e32 v[74:75], 0
	v_mov_b64_e32 v[76:77], 0
	v_mov_b64_e32 v[86:87], 0
	v_mov_b64_e32 v[88:89], 0
	v_mov_b64_e32 v[90:91], 0
	v_mov_b64_e32 v[92:93], 0
	v_mov_b64_e32 v[102:103], 0
	v_mov_b64_e32 v[104:105], 0
	v_mov_b64_e32 v[106:107], 0
	v_mov_b64_e32 v[108:109], 0
	v_mov_b64_e32 v[118:119], 0
	v_mov_b64_e32 v[120:121], 0
	v_mov_b64_e32 v[122:123], 0
	v_mov_b64_e32 v[124:125], 0
	v_mov_b64_e32 v[126:127], 0
	v_mov_b64_e32 v[128:129], 0
	v_readfirstlane_b32 s98, v228
	s_lshr_b32 s98, s98, 8
	s_cmp_eq_u32 s98, 0
	s_cbranch_scc0 .Lprio_skip_0
	s_setprio 1

.LBB0_146:
	s_ashr_i32 s29, s28, 31
	v_cmp_lt_i64_e32 vcc, s[22:23], v[198:199]
	s_lshl_b64 s[22:23], s[28:29], 19
	s_add_u32 s40, s30, s22
	s_addc_u32 s41, s31, s23
	s_and_b64 s[22:23], vcc, exec
	s_cselect_b32 s12, s41, s19
	s_cselect_b32 s29, s40, s18
	s_ashr_i32 s9, s8, 31
	s_lshl_b64 s[22:23], s[8:9], 19
	s_add_u32 s42, s49, s22
	s_addc_u32 s43, s50, s23
	s_and_b64 s[22:23], vcc, exec
	s_cselect_b32 s9, s43, s17
	s_cselect_b32 s34, s42, s16
	s_add_u32 s61, s16, 0x100
	s_addc_u32 s79, s17, 0
	s_add_u32 s16, s18, 0x40080
	v_mov_b32_e32 v0, 0
	s_addc_u32 s17, s19, 0
	s_mov_b32 s82, -2
	v_mov_b32_e32 v1, v0
	v_mov_b64_e32 v[2:3], 0
	v_mov_b64_e32 v[8:9], 0
	v_mov_b64_e32 v[10:11], 0
	v_mov_b64_e32 v[18:19], 0
	v_mov_b64_e32 v[20:21], 0
	v_mov_b64_e32 v[26:27], 0
	v_mov_b64_e32 v[28:29], 0
	s_waitcnt lgkmcnt(0)
	v_mov_b64_e32 v[34:35], 0
	v_mov_b64_e32 v[36:37], 0
	v_mov_b64_e32 v[42:43], 0
	v_mov_b64_e32 v[44:45], 0
	v_mov_b64_e32 v[50:51], 0
	v_mov_b64_e32 v[52:53], 0
	v_mov_b64_e32 v[58:59], 0
	v_mov_b64_e32 v[60:61], 0
	v_mov_b64_e32 v[4:5], 0
	v_mov_b64_e32 v[6:7], 0
	v_mov_b64_e32 v[12:13], 0
	v_mov_b64_e32 v[14:15], 0
	v_mov_b64_e32 v[22:23], 0
	v_mov_b64_e32 v[24:25], 0
	v_mov_b64_e32 v[30:31], 0
	v_mov_b64_e32 v[32:33], 0
	v_mov_b64_e32 v[38:39], 0
	v_mov_b64_e32 v[40:41], 0
	v_mov_b64_e32 v[46:47], 0
	v_mov_b64_e32 v[48:49], 0
	v_mov_b64_e32 v[54:55], 0
	v_mov_b64_e32 v[56:57], 0
	v_mov_b64_e32 v[62:63], 0
	v_mov_b64_e32 v[64:65], 0
	v_mov_b64_e32 v[66:67], 0
	v_mov_b64_e32 v[68:69], 0
	v_mov_b64_e32 v[74:75], 0
	v_mov_b64_e32 v[76:77], 0
	v_mov_b64_e32 v[82:83], 0
	v_mov_b64_e32 v[84:85], 0
	v_mov_b64_e32 v[90:91], 0
	v_mov_b64_e32 v[92:93], 0
	v_mov_b64_e32 v[98:99], 0
	v_mov_b64_e32 v[100:101], 0
	v_mov_b64_e32 v[106:107], 0
	v_mov_b64_e32 v[108:109], 0
	v_mov_b64_e32 v[114:115], 0
	v_mov_b64_e32 v[116:117], 0
	v_mov_b64_e32 v[122:123], 0
	v_mov_b64_e32 v[124:125], 0
	v_mov_b64_e32 v[70:71], 0
	v_mov_b64_e32 v[72:73], 0
	v_mov_b64_e32 v[78:79], 0
	v_mov_b64_e32 v[80:81], 0
	v_mov_b64_e32 v[86:87], 0
	v_mov_b64_e32 v[88:89], 0
	v_mov_b64_e32 v[94:95], 0
	v_mov_b64_e32 v[96:97], 0
	v_mov_b64_e32 v[102:103], 0
	v_mov_b64_e32 v[104:105], 0
	v_mov_b64_e32 v[110:111], 0
	v_mov_b64_e32 v[112:113], 0
	v_mov_b64_e32 v[118:119], 0
	v_mov_b64_e32 v[120:121], 0
	v_mov_b64_e32 v[126:127], 0
	v_mov_b64_e32 v[128:129], 0
	v_readfirstlane_b32 s98, v228
	s_lshr_b32 s98, s98, 8
	s_cmp_eq_u32 s98, 0
	s_cbranch_scc0 .Lprio_skip_1
	s_setprio 1

.LBB0_173:
	s_ashr_i32 s9, s8, 31
	v_cmp_lt_i64_e32 vcc, s[14:15], v[202:203]
	s_lshl_b64 s[14:15], s[8:9], 19
	s_add_u32 s14, s96, s14
	s_addc_u32 s15, s97, s15
	s_and_b64 s[16:17], vcc, exec
	s_cselect_b32 s9, s15, s23
	s_cselect_b32 s12, s14, s22
	s_ashr_i32 s5, s4, 31
	s_lshl_b64 s[16:17], s[4:5], 19
	s_add_u32 s16, s50, s16
	s_addc_u32 s17, s51, s17
	s_and_b64 s[42:43], vcc, exec
	s_cselect_b32 s5, s17, s41
	s_cselect_b32 s34, s16, s40
	s_add_u32 s61, s40, 0x100
	v_mov_b32_e32 v0, 0
	s_addc_u32 s79, s41, 0
	s_mov_b32 s82, -2
	v_mov_b32_e32 v1, v0
	v_mov_b64_e32 v[2:3], 0
	v_mov_b64_e32 v[4:5], 0
	v_mov_b64_e32 v[6:7], 0
	v_mov_b64_e32 v[8:9], 0
	v_mov_b64_e32 v[10:11], 0
	v_mov_b64_e32 v[12:13], 0
	v_mov_b64_e32 v[14:15], 0
	v_mov_b64_e32 v[22:23], 0
	v_mov_b64_e32 v[24:25], 0
	v_mov_b64_e32 v[26:27], 0
	v_mov_b64_e32 v[28:29], 0
	v_mov_b64_e32 v[34:35], 0
	v_mov_b64_e32 v[36:37], 0
	v_mov_b64_e32 v[42:43], 0
	v_mov_b64_e32 v[44:45], 0
	v_mov_b64_e32 v[18:19], 0
	v_mov_b64_e32 v[20:21], 0
	v_mov_b64_e32 v[30:31], 0
	v_mov_b64_e32 v[32:33], 0
	v_mov_b64_e32 v[38:39], 0
	v_mov_b64_e32 v[40:41], 0
	v_mov_b64_e32 v[46:47], 0
	v_mov_b64_e32 v[48:49], 0
	v_mov_b64_e32 v[50:51], 0
	v_mov_b64_e32 v[52:53], 0
	v_mov_b64_e32 v[54:55], 0
	v_mov_b64_e32 v[56:57], 0
	v_mov_b64_e32 v[58:59], 0
	v_mov_b64_e32 v[60:61], 0
	v_mov_b64_e32 v[62:63], 0
	v_mov_b64_e32 v[64:65], 0
	v_mov_b64_e32 v[66:67], 0
	v_mov_b64_e32 v[68:69], 0
	v_mov_b64_e32 v[70:71], 0
	v_mov_b64_e32 v[72:73], 0
	v_mov_b64_e32 v[78:79], 0
	v_mov_b64_e32 v[80:81], 0
	v_mov_b64_e32 v[82:83], 0
	v_mov_b64_e32 v[84:85], 0
	v_mov_b64_e32 v[94:95], 0
	v_mov_b64_e32 v[96:97], 0
	v_mov_b64_e32 v[98:99], 0
	v_mov_b64_e32 v[100:101], 0
	v_mov_b64_e32 v[110:111], 0
	v_mov_b64_e32 v[112:113], 0
	v_mov_b64_e32 v[114:115], 0
	v_mov_b64_e32 v[116:117], 0
	v_mov_b64_e32 v[74:75], 0
	v_mov_b64_e32 v[76:77], 0
	v_mov_b64_e32 v[86:87], 0
	v_mov_b64_e32 v[88:89], 0
	v_mov_b64_e32 v[90:91], 0
	v_mov_b64_e32 v[92:93], 0
	v_mov_b64_e32 v[102:103], 0
	v_mov_b64_e32 v[104:105], 0
	v_mov_b64_e32 v[106:107], 0
	v_mov_b64_e32 v[108:109], 0
	v_mov_b64_e32 v[118:119], 0
	v_mov_b64_e32 v[120:121], 0
	v_mov_b64_e32 v[122:123], 0
	v_mov_b64_e32 v[124:125], 0
	v_mov_b64_e32 v[126:127], 0
	v_mov_b64_e32 v[128:129], 0
	v_readfirstlane_b32 s98, v228
	s_lshr_b32 s98, s98, 8
	s_cmp_eq_u32 s98, 0
	s_cbranch_scc0 .Lprio_skip_2
	s_setprio 1

.LBB0_201:
	v_lshrrev_b32_e32 v18, 1, v0
	v_and_b32_e32 v18, 24, v18
	v_and_b32_e32 v7, 15, v0
	v_lshlrev_b32_e32 v19, 1, v18
	v_lshlrev_b32_e32 v0, 2, v0
	v_lshl_or_b32 v240, s2, 6, v7
	v_lshl_or_b32 v7, v7, 6, v19
	s_lshl_b32 s2, s2, 13
	v_and_b32_e32 v0, 32, v0
	v_lshl_add_u64 v[8:9], s[16:17], 0, v[16:17]
	v_mov_b32_e32 v213, v17
	v_bitop3_b32 v19, v7, s2, v0 bitop3:0xde
	s_lshl_b32 s2, s4, 5
	v_lshl_add_u64 v[10:11], s[16:17], 0, v[212:213]
	v_mov_b32_e32 v209, v17
	s_and_b32 s2, s2, 0x60
	s_add_i32 m0, s52, 0x18000
	v_lshl_add_u64 v[8:9], v[8:9], 0, s[10:11]
	v_lshl_add_u64 v[12:13], s[18:19], 0, v[208:209]
	v_mov_b32_e32 v211, v17
	s_lshl_b32 s4, s2, 7
	s_waitcnt vmcnt(4)
	s_barrier
	global_load_lds_dwordx4 v[8:9], off
	v_lshl_add_u64 v[8:9], v[10:11], 0, s[10:11]
	s_add_i32 m0, s52, 0x1a000
	s_add_i32 s61, s52, 0x8000
	s_add_i32 s35, s52, 0xa000
	v_lshl_add_u64 v[14:15], s[18:19], 0, v[210:211]
	v_bitop3_b32 v241, v7, s4, v0 bitop3:0xde
	global_load_lds_dwordx4 v[8:9], off
	v_lshl_add_u64 v[8:9], v[12:13], 0, s[10:11]
	s_mov_b32 m0, s61
	s_add_u32 s4, s16, 0x20080
	global_load_lds_dwordx4 v[8:9], off
	v_lshl_add_u64 v[8:9], v[14:15], 0, s[10:11]
	s_mov_b32 m0, s35
	s_addc_u32 s5, s17, 0
	global_load_lds_dwordx4 v[8:9], off
	s_add_i32 m0, s52, 0x1c000
	v_lshl_add_u64 v[8:9], s[4:5], 0, v[16:17]
	global_load_lds_dwordx4 v[8:9], off
	v_lshl_add_u64 v[8:9], s[4:5], 0, v[212:213]
	s_add_i32 m0, s52, 0x1e000
	v_lshlrev_b32_e32 v0, 13, v4
	global_load_lds_dwordx4 v[8:9], off
	v_and_b32_e32 v0, 0xffffc000, v0
	v_lshl_add_u32 v0, v5, 10, v0
	v_and_b32_e32 v4, 1, v4
	v_lshl_or_b32 v0, v4, 6, v0
	v_lshl_add_u32 v214, v6, 1, v0
	v_lshlrev_b32_e32 v0, 13, v1
	v_and_b32_e32 v0, 0xffffc000, v0
	s_waitcnt vmcnt(6)
	v_lshl_add_u32 v0, v2, 10, v0
	v_and_b32_e32 v1, 1, v1
	v_or_b32_e32 v242, s2, v18
	v_lshl_or_b32 v0, v1, 6, v0
	v_mov_b32_e32 v18, 0
	s_ashr_i32 s82, s29, 31
	v_mov_b32_e32 v215, v17
	v_lshl_add_u32 v216, v3, 1, v0
	v_mov_b32_e32 v217, v17
	s_mov_b32 s84, 0
	v_add_u32_e32 v243, 0, v19
	s_mov_b32 s83, 0
	v_mov_b32_e32 v19, v18
	v_mov_b64_e32 v[20:21], 0
	v_mov_b64_e32 v[22:23], 0
	v_mov_b64_e32 v[24:25], 0
	v_mov_b64_e32 v[26:27], 0
	v_mov_b64_e32 v[28:29], 0
	v_mov_b64_e32 v[30:31], 0
	v_mov_b64_e32 v[32:33], 0
	s_waitcnt lgkmcnt(0)
	v_mov_b64_e32 v[34:35], 0
	v_mov_b64_e32 v[36:37], 0
	v_mov_b64_e32 v[38:39], 0
	v_mov_b64_e32 v[40:41], 0
	v_mov_b64_e32 v[42:43], 0
	v_mov_b64_e32 v[44:45], 0
	v_mov_b64_e32 v[46:47], 0
	v_mov_b64_e32 v[48:49], 0
	v_mov_b64_e32 v[50:51], 0
	v_mov_b64_e32 v[52:53], 0
	v_mov_b64_e32 v[54:55], 0
	v_mov_b64_e32 v[56:57], 0
	v_mov_b64_e32 v[58:59], 0
	v_mov_b64_e32 v[60:61], 0
	v_mov_b64_e32 v[62:63], 0
	v_mov_b64_e32 v[64:65], 0
	v_mov_b64_e32 v[66:67], 0
	v_mov_b64_e32 v[68:69], 0
	v_mov_b64_e32 v[70:71], 0
	v_mov_b64_e32 v[72:73], 0
	v_mov_b64_e32 v[74:75], 0
	v_mov_b64_e32 v[76:77], 0
	v_mov_b64_e32 v[78:79], 0
	v_mov_b64_e32 v[80:81], 0
	v_mov_b64_e32 v[82:83], 0
	v_mov_b64_e32 v[84:85], 0
	v_mov_b64_e32 v[86:87], 0
	v_mov_b64_e32 v[88:89], 0
	v_mov_b64_e32 v[90:91], 0
	v_mov_b64_e32 v[92:93], 0
	v_mov_b64_e32 v[94:95], 0
	v_mov_b64_e32 v[96:97], 0
	v_mov_b64_e32 v[98:99], 0
	v_mov_b64_e32 v[100:101], 0
	v_mov_b64_e32 v[102:103], 0
	v_mov_b64_e32 v[104:105], 0
	v_mov_b64_e32 v[106:107], 0
	v_mov_b64_e32 v[108:109], 0
	v_mov_b64_e32 v[110:111], 0
	v_mov_b64_e32 v[112:113], 0
	v_mov_b64_e32 v[114:115], 0
	v_mov_b64_e32 v[116:117], 0
	v_mov_b64_e32 v[118:119], 0
	v_mov_b64_e32 v[120:121], 0
	v_mov_b64_e32 v[122:123], 0
	v_mov_b64_e32 v[124:125], 0
	v_mov_b64_e32 v[126:127], 0
	v_mov_b64_e32 v[128:129], 0
	v_mov_b64_e32 v[130:131], 0
	v_mov_b64_e32 v[132:133], 0
	v_mov_b64_e32 v[134:135], 0
	v_mov_b64_e32 v[136:137], 0
	v_mov_b64_e32 v[138:139], 0
	v_mov_b64_e32 v[140:141], 0
	v_mov_b64_e32 v[142:143], 0
	v_mov_b64_e32 v[144:145], 0
	s_barrier
	s_branch .LBB0_204

.LBB0_324:
	s_mov_b64 s[8:9], -1
	s_and_b64 vcc, exec, s[38:39]
	s_cbranch_vccz .LBB0_203
	s_cmp_lt_i32 s84, 3
	s_cbranch_scc1 .LBB0_202
	v_mov_b32_e32 v18, 0
	v_mov_b32_e32 v19, v18
	v_mov_b64_e32 v[20:21], 0
	v_mov_b64_e32 v[22:23], 0
	v_mov_b64_e32 v[24:25], 0
	v_mov_b64_e32 v[26:27], 0
	v_mov_b64_e32 v[28:29], 0
	v_mov_b64_e32 v[30:31], 0
	v_mov_b64_e32 v[32:33], 0
	v_mov_b64_e32 v[34:35], 0
	v_mov_b64_e32 v[36:37], 0
	v_mov_b64_e32 v[38:39], 0
	v_mov_b64_e32 v[40:41], 0
	v_mov_b64_e32 v[42:43], 0
	v_mov_b64_e32 v[44:45], 0
	v_mov_b64_e32 v[46:47], 0
	v_mov_b64_e32 v[48:49], 0
	v_mov_b64_e32 v[50:51], 0
	v_mov_b64_e32 v[52:53], 0
	v_mov_b64_e32 v[54:55], 0
	v_mov_b64_e32 v[56:57], 0
	v_mov_b64_e32 v[58:59], 0
	v_mov_b64_e32 v[60:61], 0
	v_mov_b64_e32 v[62:63], 0
	v_mov_b64_e32 v[64:65], 0
	v_mov_b64_e32 v[66:67], 0
	v_mov_b64_e32 v[68:69], 0
	v_mov_b64_e32 v[70:71], 0
	v_mov_b64_e32 v[72:73], 0
	v_mov_b64_e32 v[74:75], 0
	v_mov_b64_e32 v[76:77], 0
	v_mov_b64_e32 v[78:79], 0
	v_mov_b64_e32 v[80:81], 0
	v_mov_b64_e32 v[82:83], 0
	v_mov_b64_e32 v[84:85], 0
	v_mov_b64_e32 v[86:87], 0
	v_mov_b64_e32 v[88:89], 0
	v_mov_b64_e32 v[90:91], 0
	v_mov_b64_e32 v[92:93], 0
	v_mov_b64_e32 v[94:95], 0
	v_mov_b64_e32 v[96:97], 0
	v_mov_b64_e32 v[98:99], 0
	v_mov_b64_e32 v[100:101], 0
	v_mov_b64_e32 v[102:103], 0
	v_mov_b64_e32 v[104:105], 0
	v_mov_b64_e32 v[106:107], 0
	v_mov_b64_e32 v[108:109], 0
	v_mov_b64_e32 v[110:111], 0
	v_mov_b64_e32 v[112:113], 0
	v_mov_b64_e32 v[114:115], 0
	v_mov_b64_e32 v[116:117], 0
	v_mov_b64_e32 v[118:119], 0
	v_mov_b64_e32 v[120:121], 0
	v_mov_b64_e32 v[122:123], 0
	v_mov_b64_e32 v[124:125], 0
	v_mov_b64_e32 v[126:127], 0
	v_mov_b64_e32 v[128:129], 0
	v_mov_b64_e32 v[130:131], 0
	v_mov_b64_e32 v[132:133], 0
	v_mov_b64_e32 v[134:135], 0
	v_mov_b64_e32 v[136:137], 0
	v_mov_b64_e32 v[138:139], 0
	v_mov_b64_e32 v[140:141], 0
	v_mov_b64_e32 v[142:143], 0
	v_mov_b64_e32 v[144:145], 0
	s_branch .LBB0_202

.LBB0_978:
	s_ashr_i32 s9, s8, 31
	v_cmp_lt_i64_e32 vcc, s[14:15], v[206:207]
	s_lshl_b64 s[14:15], s[8:9], 19
	s_add_u32 s14, s30, s14
	s_addc_u32 s15, s31, s15
	s_and_b64 s[16:17], vcc, exec
	s_cselect_b32 s9, s15, s23
	s_cselect_b32 s56, s14, s22
	s_ashr_i32 s5, s4, 31
	s_lshl_b64 s[16:17], s[4:5], 19
	s_add_u32 s16, s44, s16
	s_addc_u32 s17, s45, s17
	s_and_b64 s[28:29], vcc, exec
	s_cselect_b32 s5, s17, s21
	s_cselect_b32 s57, s16, s20
	s_add_u32 s58, s20, 0x100
	s_addc_u32 s59, s21, 0
	s_add_u32 s20, s22, 0x40080
	v_mov_b32_e32 v26, 0
	s_addc_u32 s21, s23, 0
	s_mov_b32 s60, -2
	v_mov_b32_e32 v27, v26
	v_mov_b64_e32 v[28:29], 0
	v_mov_b64_e32 v[38:39], 0
	v_mov_b64_e32 v[40:41], 0
	v_mov_b64_e32 v[46:47], 0
	v_mov_b64_e32 v[48:49], 0
	v_mov_b64_e32 v[58:59], 0
	v_mov_b64_e32 v[60:61], 0
	v_mov_b64_e32 v[82:83], 0
	v_mov_b64_e32 v[84:85], 0
	v_mov_b64_e32 v[86:87], 0
	v_mov_b64_e32 v[88:89], 0
	v_mov_b64_e32 v[90:91], 0
	v_mov_b64_e32 v[92:93], 0
	v_mov_b64_e32 v[94:95], 0
	v_mov_b64_e32 v[96:97], 0
	v_mov_b64_e32 v[0:1], 0
	v_mov_b64_e32 v[2:3], 0
	v_mov_b64_e32 v[4:5], 0
	v_mov_b64_e32 v[6:7], 0
	v_mov_b64_e32 v[8:9], 0
	v_mov_b64_e32 v[10:11], 0
	v_mov_b64_e32 v[12:13], 0
	v_mov_b64_e32 v[14:15], 0
	v_mov_b64_e32 v[18:19], 0
	v_mov_b64_e32 v[20:21], 0
	v_mov_b64_e32 v[22:23], 0
	v_mov_b64_e32 v[24:25], 0
	v_mov_b64_e32 v[30:31], 0
	v_mov_b64_e32 v[32:33], 0
	s_waitcnt lgkmcnt(0)
	v_mov_b64_e32 v[34:35], 0
	v_mov_b64_e32 v[36:37], 0
	v_mov_b64_e32 v[98:99], 0
	v_mov_b64_e32 v[100:101], 0
	v_mov_b64_e32 v[102:103], 0
	v_mov_b64_e32 v[104:105], 0
	v_mov_b64_e32 v[106:107], 0
	v_mov_b64_e32 v[108:109], 0
	v_mov_b64_e32 v[110:111], 0
	v_mov_b64_e32 v[112:113], 0
	v_mov_b64_e32 v[114:115], 0
	v_mov_b64_e32 v[116:117], 0
	v_mov_b64_e32 v[118:119], 0
	v_mov_b64_e32 v[120:121], 0
	v_mov_b64_e32 v[122:123], 0
	v_mov_b64_e32 v[124:125], 0
	v_mov_b64_e32 v[126:127], 0
	v_mov_b64_e32 v[128:129], 0
	v_mov_b64_e32 v[42:43], 0
	v_mov_b64_e32 v[44:45], 0
	v_mov_b64_e32 v[50:51], 0
	v_mov_b64_e32 v[52:53], 0
	v_mov_b64_e32 v[54:55], 0
	v_mov_b64_e32 v[56:57], 0
	v_mov_b64_e32 v[62:63], 0
	v_mov_b64_e32 v[64:65], 0
	v_mov_b64_e32 v[66:67], 0
	v_mov_b64_e32 v[68:69], 0
	v_mov_b64_e32 v[70:71], 0
	v_mov_b64_e32 v[72:73], 0
	v_mov_b64_e32 v[74:75], 0
	v_mov_b64_e32 v[76:77], 0
	v_mov_b64_e32 v[78:79], 0
	v_mov_b64_e32 v[80:81], 0
	v_readfirstlane_b32 s98, v228
	s_lshr_b32 s98, s98, 8
	s_cmp_eq_u32 s98, 0
	s_cbranch_scc0 .Lprio_skip_4
	s_setprio 1
